# v25 + write-through (sc1) output stores in the VALU-bound phases (hyena final stage, rg3 output norm, hytrans)
# speedup vs baseline: 1.0075x; 1.0075x over previous
.LBB0_499:
	s_or_b64 exec, exec, s[4:5]
	s_waitcnt vmcnt(0)
	v_lshlrev_b32_e32 v21, 16, v33
	v_lshlrev_b32_e32 v19, 16, v37
	v_lshlrev_b32_e32 v20, 16, v47
	v_lshlrev_b32_e32 v18, 16, v80
	v_lshlrev_b32_e32 v16, 16, v12
	v_fma_f32 v21, v148, v21, v149
	v_and_b32_e32 v12, 0xffff0000, v12
	v_fmac_f32_e32 v21, v45, v16
	v_fma_f32 v16, v148, v16, v149
	v_lshlrev_b32_e32 v17, 16, v13
	v_fmac_f32_e32 v16, v45, v12
	v_fma_f32 v28, v148, v12, v149
	v_and_b32_e32 v13, 0xffff0000, v13
	v_fmac_f32_e32 v16, v44, v17
	v_fmac_f32_e32 v28, v45, v17
	v_fma_f32 v17, v148, v17, v149
	v_lshlrev_b32_e32 v22, 16, v14
	v_fmac_f32_e32 v17, v45, v13
	v_fma_f32 v29, v148, v13, v149
	v_and_b32_e32 v14, 0xffff0000, v14
	v_fmac_f32_e32 v17, v44, v22
	v_fmac_f32_e32 v29, v45, v22
	v_fma_f32 v22, v148, v22, v149
	v_lshlrev_b32_e32 v23, 16, v15
	v_fmac_f32_e32 v22, v45, v14
	v_fma_f32 v30, v148, v14, v149
	v_and_b32_e32 v15, 0xffff0000, v15
	v_fmac_f32_e32 v22, v44, v23
	v_fmac_f32_e32 v30, v45, v23
	v_fma_f32 v23, v148, v23, v149
	s_waitcnt vmcnt(2)
	v_lshlrev_b32_e32 v24, 16, v8
	v_fmac_f32_e32 v23, v45, v15
	v_fma_f32 v31, v148, v15, v149
	v_and_b32_e32 v8, 0xffff0000, v8
	v_fmac_f32_e32 v23, v44, v24
	v_fmac_f32_e32 v31, v45, v24
	v_fma_f32 v24, v148, v24, v149
	v_lshlrev_b32_e32 v25, 16, v9
	v_fmac_f32_e32 v24, v45, v8
	v_fma_f32 v37, v148, v8, v149
	v_and_b32_e32 v9, 0xffff0000, v9
	v_fmac_f32_e32 v24, v44, v25
	v_fmac_f32_e32 v37, v45, v25
	v_fma_f32 v25, v148, v25, v149
	v_lshlrev_b32_e32 v26, 16, v10
	v_fmac_f32_e32 v25, v45, v9
	v_fma_f32 v39, v148, v9, v149
	v_and_b32_e32 v10, 0xffff0000, v10
	v_lshlrev_b32_e32 v27, 16, v11
	v_fmac_f32_e32 v25, v44, v26
	v_fmac_f32_e32 v39, v45, v26
	v_fma_f32 v26, v148, v26, v149
	v_and_b32_e32 v11, 0xffff0000, v11
	v_fmac_f32_e32 v31, v44, v8
	v_fmac_f32_e32 v37, v44, v9
	v_fmac_f32_e32 v39, v44, v10
	v_fmac_f32_e32 v26, v45, v10
	v_fma_f32 v8, v148, v10, v149
	v_fma_f32 v9, v148, v27, v149
	s_waitcnt vmcnt(1)
	v_and_b32_e32 v10, 0xffff0000, v4
	v_fmac_f32_e32 v21, v44, v12
	v_fmac_f32_e32 v28, v44, v13
	v_fmac_f32_e32 v9, v45, v11
	v_lshlrev_b32_e32 v13, 16, v4
	v_mov_b32_e32 v12, v10
	v_fmac_f32_e32 v29, v44, v14
	v_fmac_f32_e32 v30, v44, v15
	v_fmac_f32_e32 v8, v45, v27
	v_fmac_f32_e32 v9, v44, v19
	v_fma_f32 v19, v148, v20, v149
	v_pk_mul_f32 v[14:15], v[44:45], v[12:13]
	v_fmac_f32_e32 v8, v44, v11
	v_and_b32_e32 v11, 16, v4
	v_add_f32_e32 v4, v15, v19
	v_and_b32_e32 v12, 0xffff0000, v5
	v_add_f32_e32 v14, v14, v4
	v_fma_f32 v15, v148, v13, v149
	v_and_b32_e32 v13, 16, v5
	v_lshlrev_b32_e32 v5, 16, v5
	v_mov_b32_e32 v4, v12
	v_fma_f32 v19, v148, v10, v149
	v_pk_mov_b32 v[10:11], v[4:5], v[10:11] op_sel:[1,0]
	v_fmac_f32_e32 v26, v44, v27
	v_pk_mul_f32 v[10:11], v[44:45], v[10:11]
	v_fma_f32 v27, v148, v12, v149
	v_add_f32_e32 v11, v11, v15
	v_add_f32_e32 v15, v10, v11
	v_pk_mul_f32 v[10:11], v[44:45], v[4:5]
	v_fma_f32 v20, v148, v5, v149
	v_add_f32_e32 v4, v11, v19
	v_add_f32_e32 v19, v10, v4
	v_and_b32_e32 v4, 0xffff0000, v6
	v_lshlrev_b32_e32 v11, 16, v6
	v_mov_b32_e32 v10, v4
	v_pk_mov_b32 v[12:13], v[10:11], v[12:13] op_sel:[1,0]
	v_and_b32_e32 v5, 16, v6
	v_pk_mul_f32 v[12:13], v[44:45], v[12:13]
	s_mov_b64 s[4:5], 0xc0000
	v_add_f32_e32 v6, v13, v20
	v_add_f32_e32 v20, v12, v6
	v_pk_mul_f32 v[12:13], v[44:45], v[10:11]
	v_and_b32_e32 v10, 0xffff0000, v7
	v_add_f32_e32 v6, v13, v27
	v_add_f32_e32 v12, v12, v6
	v_fma_f32 v13, v148, v11, v149
	v_and_b32_e32 v11, 16, v7
	v_lshlrev_b32_e32 v7, 16, v7
	v_mov_b32_e32 v6, v10
	v_fma_f32 v27, v148, v4, v149
	v_pk_mov_b32 v[4:5], v[6:7], v[4:5] op_sel:[1,0]
	v_fma_f32 v47, v148, v7, v149
	v_pk_mul_f32 v[4:5], v[44:45], v[4:5]
	v_fma_f32 v81, v148, v10, v149
	v_add_f32_e32 v5, v5, v13
	v_add_f32_e32 v13, v4, v5
	v_pk_mul_f32 v[4:5], v[44:45], v[6:7]
	s_waitcnt vmcnt(0)
	v_lshlrev_b32_e32 v7, 16, v0
	v_add_f32_e32 v5, v5, v27
	v_add_f32_e32 v27, v4, v5
	v_and_b32_e32 v4, 0xffff0000, v0
	v_mov_b32_e32 v6, v4
	v_pk_mov_b32 v[10:11], v[6:7], v[10:11] op_sel:[1,0]
	v_and_b32_e32 v5, 16, v0
	v_pk_mul_f32 v[10:11], v[44:45], v[10:11]
	s_nop 0
	v_add_f32_e32 v0, v11, v47
	v_add_f32_e32 v47, v10, v0
	v_pk_mul_f32 v[10:11], v[44:45], v[6:7]
	v_and_b32_e32 v6, 0xffff0000, v1
	v_add_f32_e32 v0, v81, v11
	v_add_f32_e32 v10, v10, v0
	v_fma_f32 v11, v148, v7, v149
	v_and_b32_e32 v7, 16, v1
	v_lshlrev_b32_e32 v1, 16, v1
	v_mov_b32_e32 v0, v6
	v_fma_f32 v81, v148, v4, v149
	v_pk_mov_b32 v[4:5], v[0:1], v[4:5] op_sel:[1,0]
	v_fma_f32 v83, v148, v6, v149
	v_pk_mul_f32 v[4:5], v[44:45], v[4:5]
	v_fma_f32 v82, v148, v1, v149
	v_add_f32_e32 v5, v5, v11
	v_add_f32_e32 v11, v4, v5
	v_pk_mul_f32 v[4:5], v[44:45], v[0:1]
	v_and_b32_e32 v1, 16, v2
	v_add_f32_e32 v0, v5, v81
	v_add_f32_e32 v81, v4, v0
	v_and_b32_e32 v0, 0xffff0000, v2
	v_lshlrev_b32_e32 v5, 16, v2
	v_mov_b32_e32 v4, v0
	v_pk_mov_b32 v[6:7], v[4:5], v[6:7] op_sel:[1,0]
	s_nop 0
	v_pk_mul_f32 v[6:7], v[44:45], v[6:7]
	s_nop 0
	v_add_f32_e32 v2, v7, v82
	v_add_f32_e32 v82, v6, v2
	v_pk_mul_f32 v[6:7], v[44:45], v[4:5]
	v_fma_f32 v5, v148, v5, v149
	v_add_f32_e32 v2, v7, v83
	v_add_f32_e32 v4, v6, v2
	v_and_b32_e32 v2, 0xffff0000, v3
	v_lshlrev_b32_e32 v3, 16, v3
	v_fma_f32 v6, v148, v0, v149
	v_pk_mov_b32 v[0:1], v[2:3], v[0:1] op_sel:[1,0]
	v_fma_f32 v7, v148, v3, v149
	v_pk_mul_f32 v[0:1], v[44:45], v[0:1]
	s_nop 0
	v_add_f32_e32 v1, v1, v5
	v_add_f32_e32 v5, v0, v1
	v_pk_mul_f32 v[0:1], v[44:45], v[2:3]
	v_mov_b32_e32 v3, v18
	v_add_f32_e32 v1, v1, v6
	v_add_f32_e32 v6, v0, v1
	v_mov_b32_e32 v0, v45
	v_mov_b32_e32 v1, v44
	v_pk_mul_f32 v[0:1], v[0:1], v[2:3]
	s_nop 0
	v_add_f32_e32 v0, v0, v7
	v_add_f32_e32 v7, v0, v1
	ds_read2_b64 v[182:185], v152 offset1:1
	ds_read2_b64 v[186:189], v152 offset0:2 offset1:3
	ds_read2_b64 v[190:193], v152 offset0:4 offset1:5
	ds_read2_b64 v[194:197], v152 offset0:6 offset1:7
	ds_read2_b64 v[198:201], v152 offset0:8 offset1:9
	ds_read2_b64 v[214:217], v152 offset0:10 offset1:11
	ds_read2_b64 v[218:221], v152 offset0:12 offset1:13
	ds_read2_b64 v[222:225], v152 offset0:14 offset1:15
	s_waitcnt lgkmcnt(7)
	v_fma_f32 v0, v150, v110, v182
	v_mul_f32_e32 v18, v21, v0
	v_fma_f32 v0, v150, v111, -v183
	v_mul_f32_e32 v14, v14, v0
	v_fma_f32 v0, v150, v102, v184
	v_mul_f32_e32 v16, v16, v0
	v_fma_f32 v0, v150, v103, -v185
	v_mul_f32_e32 v15, v15, v0
	s_waitcnt lgkmcnt(6)
	v_fma_f32 v0, v150, v94, v186
	v_mul_f32_e32 v21, v28, v0
	v_fma_f32 v0, v150, v95, -v187
	v_mul_f32_e32 v19, v19, v0
	v_fma_f32 v0, v150, v88, v188
	v_mul_f32_e32 v17, v17, v0
	v_fma_f32 v0, v150, v89, -v189
	v_mul_f32_e32 v20, v20, v0
	s_waitcnt lgkmcnt(5)
	v_fma_f32 v0, v150, v112, v190
	v_mul_f32_e32 v28, v29, v0
	v_fma_f32 v0, v150, v113, -v191
	v_mul_f32_e32 v12, v12, v0
	v_fma_f32 v0, v150, v104, v192
	v_mul_f32_e32 v22, v22, v0
	v_fma_f32 v0, v150, v105, -v193
	v_mul_f32_e32 v13, v13, v0
	s_waitcnt lgkmcnt(4)
	v_fma_f32 v0, v150, v96, v194
	v_mul_f32_e32 v29, v30, v0
	v_fma_f32 v0, v150, v97, -v195
	v_mul_f32_e32 v27, v27, v0
	v_fma_f32 v0, v150, v90, v196
	v_mul_f32_e32 v23, v23, v0
	v_fma_f32 v0, v150, v91, -v197
	v_mul_f32_e32 v30, v47, v0
	s_waitcnt lgkmcnt(3)
	v_fma_f32 v0, v150, v114, v198
	v_mul_f32_e32 v31, v31, v0
	v_fma_f32 v0, v150, v115, -v199
	v_mul_f32_e32 v47, v10, v0
	v_fma_f32 v0, v150, v106, v200
	v_mul_f32_e32 v10, v24, v0
	v_fma_f32 v0, v150, v107, -v201
	v_mul_f32_e32 v24, v11, v0
	s_waitcnt lgkmcnt(2)
	v_fma_f32 v0, v150, v98, v214
	v_mul_f32_e32 v11, v37, v0
	v_fma_f32 v0, v150, v99, -v215
	v_mul_f32_e32 v37, v81, v0
	v_fma_f32 v0, v150, v92, v216
	v_mul_f32_e32 v25, v25, v0
	v_fma_f32 v0, v150, v93, -v217
	v_mul_f32_e32 v81, v82, v0
	s_waitcnt lgkmcnt(1)
	v_fma_f32 v0, v150, v116, v218
	v_mul_f32_e32 v39, v39, v0
	v_fma_f32 v0, v150, v117, -v219
	v_mul_f32_e32 v82, v4, v0
	v_fma_f32 v0, v150, v108, v220
	v_mul_f32_e32 v26, v26, v0
	v_fma_f32 v0, v150, v109, -v221
	v_mul_f32_e32 v83, v5, v0
	s_waitcnt lgkmcnt(0)
	v_fma_f32 v0, v150, v100, v222
	v_mul_f32_e32 v8, v8, v0
	v_fma_f32 v0, v150, v101, -v223
	v_mul_f32_e32 v84, v6, v0
	v_fma_f32 v0, v150, v86, v224
	v_mul_f32_e32 v9, v9, v0
	v_fma_f32 v0, v150, v87, -v225
	v_mul_f32_e32 v85, v7, v0
	v_cvt_pk_bf16_f32 v0, v18, v16
	v_cvt_pk_bf16_f32 v1, v21, v17
	v_cvt_pk_bf16_f32 v2, v28, v22
	v_cvt_pk_bf16_f32 v3, v29, v23
	v_lshl_add_u64 v[16:17], v[78:79], 0, v[172:173]
	v_cvt_pk_bf16_f32 v4, v31, v10
	v_cvt_pk_bf16_f32 v5, v11, v25
	v_cvt_pk_bf16_f32 v6, v39, v26
	v_cvt_pk_bf16_f32 v7, v8, v9
	v_cvt_pk_bf16_f32 v8, v14, v15
	v_cvt_pk_bf16_f32 v9, v19, v20
	v_cvt_pk_bf16_f32 v10, v12, v13
	v_cvt_pk_bf16_f32 v11, v27, v30
	v_cvt_pk_bf16_f32 v12, v47, v24
	v_cvt_pk_bf16_f32 v13, v37, v81
	v_cvt_pk_bf16_f32 v14, v82, v83
	v_cvt_pk_bf16_f32 v15, v84, v85
	global_store_dwordx4 v[16:17], v[0:3], off sc1
	global_store_dwordx4 v[16:17], v[4:7], off offset:16 sc1
	s_nop 0
	v_add_co_u32_e32 v2, vcc, 0xc0000, v16
	v_lshl_add_u64 v[0:1], v[16:17], 0, s[4:5]
	s_nop 0
	v_addc_co_u32_e32 v3, vcc, 0, v17, vcc
	global_store_dwordx4 v[2:3], v[8:11], off sc1
	global_store_dwordx4 v[0:1], v[12:15], off offset:16 sc1

.LBB0_601:
	s_or_b64 exec, exec, s[4:5]
	s_waitcnt vmcnt(0)
	v_lshlrev_b32_e32 v21, 16, v157
	v_lshlrev_b32_e32 v19, 16, v158
	v_lshlrev_b32_e32 v20, 16, v159
	v_lshlrev_b32_e32 v18, 16, v160
	v_lshlrev_b32_e32 v16, 16, v12
	v_fma_f32 v21, v148, v21, v149
	v_and_b32_e32 v12, 0xffff0000, v12
	v_fmac_f32_e32 v21, v45, v16
	v_fma_f32 v16, v148, v16, v149
	v_lshlrev_b32_e32 v17, 16, v13
	v_fmac_f32_e32 v16, v45, v12
	v_fma_f32 v28, v148, v12, v149
	v_and_b32_e32 v13, 0xffff0000, v13
	v_fmac_f32_e32 v16, v44, v17
	v_fmac_f32_e32 v28, v45, v17
	v_fma_f32 v17, v148, v17, v149
	v_lshlrev_b32_e32 v22, 16, v14
	v_fmac_f32_e32 v17, v45, v13
	v_fma_f32 v29, v148, v13, v149
	v_and_b32_e32 v14, 0xffff0000, v14
	v_fmac_f32_e32 v17, v44, v22
	v_fmac_f32_e32 v29, v45, v22
	v_fma_f32 v22, v148, v22, v149
	v_lshlrev_b32_e32 v23, 16, v15
	v_fmac_f32_e32 v22, v45, v14
	v_fma_f32 v30, v148, v14, v149
	v_and_b32_e32 v15, 0xffff0000, v15
	v_fmac_f32_e32 v22, v44, v23
	v_fmac_f32_e32 v30, v45, v23
	v_fma_f32 v23, v148, v23, v149
	v_lshlrev_b32_e32 v24, 16, v8
	v_fmac_f32_e32 v23, v45, v15
	v_fma_f32 v31, v148, v15, v149
	v_and_b32_e32 v8, 0xffff0000, v8
	v_fmac_f32_e32 v23, v44, v24
	v_fmac_f32_e32 v31, v45, v24
	v_fma_f32 v24, v148, v24, v149
	v_lshlrev_b32_e32 v25, 16, v9
	v_fmac_f32_e32 v24, v45, v8
	v_fma_f32 v41, v148, v8, v149
	v_and_b32_e32 v9, 0xffff0000, v9
	v_fmac_f32_e32 v24, v44, v25
	v_fmac_f32_e32 v41, v45, v25
	v_fma_f32 v25, v148, v25, v149
	v_lshlrev_b32_e32 v26, 16, v10
	v_fmac_f32_e32 v25, v45, v9
	v_fma_f32 v58, v148, v9, v149
	v_and_b32_e32 v10, 0xffff0000, v10
	v_lshlrev_b32_e32 v27, 16, v11
	v_fmac_f32_e32 v25, v44, v26
	v_fmac_f32_e32 v58, v45, v26
	v_fma_f32 v26, v148, v26, v149
	v_and_b32_e32 v11, 0xffff0000, v11
	v_fmac_f32_e32 v31, v44, v8
	v_fmac_f32_e32 v41, v44, v9
	v_fmac_f32_e32 v58, v44, v10
	v_fmac_f32_e32 v26, v45, v10
	v_fma_f32 v8, v148, v10, v149
	v_fma_f32 v9, v148, v27, v149
	s_waitcnt vmcnt(0)
	v_and_b32_e32 v10, 0xffff0000, v4
	v_fmac_f32_e32 v21, v44, v12
	v_fmac_f32_e32 v28, v44, v13
	v_fmac_f32_e32 v9, v45, v11
	v_lshlrev_b32_e32 v13, 16, v4
	v_mov_b32_e32 v12, v10
	v_fmac_f32_e32 v29, v44, v14
	v_fmac_f32_e32 v30, v44, v15
	v_fmac_f32_e32 v8, v45, v27
	v_fmac_f32_e32 v9, v44, v19
	v_fma_f32 v19, v148, v20, v149
	v_pk_mul_f32 v[14:15], v[44:45], v[12:13]
	v_fmac_f32_e32 v8, v44, v11
	v_and_b32_e32 v11, 16, v4
	v_add_f32_e32 v4, v15, v19
	v_and_b32_e32 v12, 0xffff0000, v5
	v_add_f32_e32 v14, v14, v4
	v_fma_f32 v15, v148, v13, v149
	v_and_b32_e32 v13, 16, v5
	v_lshlrev_b32_e32 v5, 16, v5
	v_mov_b32_e32 v4, v12
	v_fma_f32 v19, v148, v10, v149
	v_pk_mov_b32 v[10:11], v[4:5], v[10:11] op_sel:[1,0]
	v_fmac_f32_e32 v26, v44, v27
	v_pk_mul_f32 v[10:11], v[44:45], v[10:11]
	v_fma_f32 v27, v148, v12, v149
	v_add_f32_e32 v11, v11, v15
	v_add_f32_e32 v15, v10, v11
	v_pk_mul_f32 v[10:11], v[44:45], v[4:5]
	v_fma_f32 v20, v148, v5, v149
	v_add_f32_e32 v4, v11, v19
	v_add_f32_e32 v19, v10, v4
	v_and_b32_e32 v4, 0xffff0000, v6
	v_lshlrev_b32_e32 v11, 16, v6
	v_mov_b32_e32 v10, v4
	v_pk_mov_b32 v[12:13], v[10:11], v[12:13] op_sel:[1,0]
	v_and_b32_e32 v5, 16, v6
	v_pk_mul_f32 v[12:13], v[44:45], v[12:13]
	s_mov_b64 s[4:5], 0xc00000
	v_add_f32_e32 v6, v13, v20
	v_add_f32_e32 v20, v12, v6
	v_pk_mul_f32 v[12:13], v[44:45], v[10:11]
	v_and_b32_e32 v10, 0xffff0000, v7
	v_add_f32_e32 v6, v13, v27
	v_add_f32_e32 v12, v12, v6
	v_fma_f32 v13, v148, v11, v149
	v_and_b32_e32 v11, 16, v7
	v_lshlrev_b32_e32 v7, 16, v7
	v_mov_b32_e32 v6, v10
	v_fma_f32 v27, v148, v4, v149
	v_pk_mov_b32 v[4:5], v[6:7], v[4:5] op_sel:[1,0]
	v_fma_f32 v59, v148, v7, v149
	v_pk_mul_f32 v[4:5], v[44:45], v[4:5]
	v_fma_f32 v60, v148, v10, v149
	v_add_f32_e32 v5, v5, v13
	v_add_f32_e32 v13, v4, v5
	v_pk_mul_f32 v[4:5], v[44:45], v[6:7]
	v_lshlrev_b32_e32 v7, 16, v0
	v_add_f32_e32 v5, v5, v27
	v_add_f32_e32 v27, v4, v5
	v_and_b32_e32 v4, 0xffff0000, v0
	v_mov_b32_e32 v6, v4
	v_pk_mov_b32 v[10:11], v[6:7], v[10:11] op_sel:[1,0]
	v_and_b32_e32 v5, 16, v0
	v_pk_mul_f32 v[10:11], v[44:45], v[10:11]
	s_nop 0
	v_add_f32_e32 v0, v11, v59
	v_add_f32_e32 v59, v10, v0
	v_pk_mul_f32 v[10:11], v[44:45], v[6:7]
	v_and_b32_e32 v6, 0xffff0000, v1
	v_add_f32_e32 v0, v60, v11
	v_add_f32_e32 v10, v10, v0
	v_fma_f32 v11, v148, v7, v149
	v_and_b32_e32 v7, 16, v1
	v_lshlrev_b32_e32 v1, 16, v1
	v_mov_b32_e32 v0, v6
	v_fma_f32 v60, v148, v4, v149
	v_pk_mov_b32 v[4:5], v[0:1], v[4:5] op_sel:[1,0]
	v_fma_f32 v94, v148, v6, v149
	v_pk_mul_f32 v[4:5], v[44:45], v[4:5]
	v_fma_f32 v61, v148, v1, v149
	v_add_f32_e32 v5, v5, v11
	v_add_f32_e32 v11, v4, v5
	v_pk_mul_f32 v[4:5], v[44:45], v[0:1]
	v_and_b32_e32 v1, 16, v2
	v_add_f32_e32 v0, v5, v60
	v_add_f32_e32 v60, v4, v0
	v_and_b32_e32 v0, 0xffff0000, v2
	v_lshlrev_b32_e32 v5, 16, v2
	v_mov_b32_e32 v4, v0
	v_pk_mov_b32 v[6:7], v[4:5], v[6:7] op_sel:[1,0]
	s_nop 0
	v_pk_mul_f32 v[6:7], v[44:45], v[6:7]
	s_nop 0
	v_add_f32_e32 v2, v7, v61
	v_add_f32_e32 v61, v6, v2
	v_pk_mul_f32 v[6:7], v[44:45], v[4:5]
	v_fma_f32 v5, v148, v5, v149
	v_add_f32_e32 v2, v7, v94
	v_add_f32_e32 v4, v6, v2
	v_and_b32_e32 v2, 0xffff0000, v3
	v_lshlrev_b32_e32 v3, 16, v3
	v_fma_f32 v6, v148, v0, v149
	v_pk_mov_b32 v[0:1], v[2:3], v[0:1] op_sel:[1,0]
	v_fma_f32 v7, v148, v3, v149
	v_pk_mul_f32 v[0:1], v[44:45], v[0:1]
	s_nop 0
	v_add_f32_e32 v1, v1, v5
	v_add_f32_e32 v5, v0, v1
	v_pk_mul_f32 v[0:1], v[44:45], v[2:3]
	v_mov_b32_e32 v3, v18
	v_add_f32_e32 v1, v1, v6
	v_add_f32_e32 v6, v0, v1
	v_pk_mul_f32 v[0:1], v[50:51], v[2:3]
	s_nop 0
	v_add_f32_e32 v0, v0, v7
	v_add_f32_e32 v7, v0, v1
	ds_read2_b64 v[182:185], v152 offset1:1
	ds_read2_b64 v[186:189], v152 offset0:2 offset1:3
	ds_read2_b64 v[190:193], v152 offset0:4 offset1:5
	ds_read2_b64 v[194:197], v152 offset0:6 offset1:7
	ds_read2_b64 v[198:201], v152 offset0:8 offset1:9
	ds_read2_b64 v[214:217], v152 offset0:10 offset1:11
	ds_read2_b64 v[218:221], v152 offset0:12 offset1:13
	ds_read2_b64 v[222:225], v152 offset0:14 offset1:15
	s_waitcnt lgkmcnt(7)
	v_fma_f32 v0, v150, v92, v182
	v_mul_f32_e32 v18, v21, v0
	v_fma_f32 v0, v150, v93, -v183
	v_mul_f32_e32 v14, v14, v0
	v_fma_f32 v0, v150, v86, v184
	v_mul_f32_e32 v16, v16, v0
	v_fma_f32 v0, v150, v87, -v185
	v_mul_f32_e32 v15, v15, v0
	s_waitcnt lgkmcnt(6)
	v_fma_f32 v0, v150, v76, v186
	v_mul_f32_e32 v21, v28, v0
	v_fma_f32 v0, v150, v77, -v187
	v_mul_f32_e32 v19, v19, v0
	v_fma_f32 v0, v150, v70, v188
	v_mul_f32_e32 v17, v17, v0
	v_fma_f32 v0, v150, v71, -v189
	v_mul_f32_e32 v20, v20, v0
	s_waitcnt lgkmcnt(5)
	v_fma_f32 v0, v150, v90, v190
	v_mul_f32_e32 v28, v29, v0
	v_fma_f32 v0, v150, v91, -v191
	v_mul_f32_e32 v12, v12, v0
	v_fma_f32 v0, v150, v82, v192
	v_mul_f32_e32 v22, v22, v0
	v_fma_f32 v0, v150, v83, -v193
	v_mul_f32_e32 v13, v13, v0
	s_waitcnt lgkmcnt(4)
	v_fma_f32 v0, v150, v74, v194
	v_mul_f32_e32 v29, v30, v0
	v_fma_f32 v0, v150, v75, -v195
	v_mul_f32_e32 v27, v27, v0
	v_fma_f32 v0, v150, v66, v196
	v_mul_f32_e32 v23, v23, v0
	v_fma_f32 v0, v150, v67, -v197
	v_mul_f32_e32 v30, v59, v0
	s_waitcnt lgkmcnt(3)
	v_fma_f32 v0, v150, v88, v198
	v_mul_f32_e32 v31, v31, v0
	v_fma_f32 v0, v150, v89, -v199
	v_mul_f32_e32 v59, v10, v0
	v_fma_f32 v0, v150, v80, v200
	v_mul_f32_e32 v10, v24, v0
	v_fma_f32 v0, v150, v81, -v201
	v_mul_f32_e32 v24, v11, v0
	s_waitcnt lgkmcnt(2)
	v_fma_f32 v0, v150, v72, v214
	v_mul_f32_e32 v11, v41, v0
	v_fma_f32 v0, v150, v73, -v215
	v_mul_f32_e32 v41, v60, v0
	v_fma_f32 v0, v150, v64, v216
	v_mul_f32_e32 v25, v25, v0
	v_fma_f32 v0, v150, v65, -v217
	v_mul_f32_e32 v60, v61, v0
	s_waitcnt lgkmcnt(1)
	v_fma_f32 v0, v150, v84, v218
	v_mul_f32_e32 v58, v58, v0
	v_fma_f32 v0, v150, v85, -v219
	v_mul_f32_e32 v61, v4, v0
	v_fma_f32 v0, v150, v78, v220
	v_mul_f32_e32 v26, v26, v0
	v_fma_f32 v0, v150, v79, -v221
	v_mul_f32_e32 v64, v5, v0
	s_waitcnt lgkmcnt(0)
	v_fma_f32 v0, v150, v68, v222
	v_mul_f32_e32 v8, v8, v0
	v_fma_f32 v0, v150, v69, -v223
	v_mul_f32_e32 v65, v6, v0
	v_fma_f32 v0, v150, v62, v224
	v_mul_f32_e32 v9, v9, v0
	v_fma_f32 v0, v150, v63, -v225
	v_mul_f32_e32 v62, v7, v0
	v_cvt_pk_bf16_f32 v0, v18, v16
	v_cvt_pk_bf16_f32 v1, v21, v17
	v_cvt_pk_bf16_f32 v2, v28, v22
	v_cvt_pk_bf16_f32 v3, v29, v23
	v_cvt_pk_bf16_f32 v4, v31, v10
	v_cvt_pk_bf16_f32 v5, v11, v25
	v_cvt_pk_bf16_f32 v6, v58, v26
	v_cvt_pk_bf16_f32 v7, v8, v9
	v_cvt_pk_bf16_f32 v8, v14, v15
	v_cvt_pk_bf16_f32 v9, v19, v20
	v_cvt_pk_bf16_f32 v10, v12, v13
	v_cvt_pk_bf16_f32 v11, v27, v30
	v_cvt_pk_bf16_f32 v12, v59, v24
	v_cvt_pk_bf16_f32 v13, v41, v60
	v_cvt_pk_bf16_f32 v14, v61, v64
	v_cvt_pk_bf16_f32 v15, v65, v62
	global_store_dwordx4 v[56:57], v[0:3], off sc1
	global_store_dwordx4 v[56:57], v[4:7], off offset:16 sc1
	s_nop 0
	v_add_co_u32_e32 v2, vcc, 0xc00000, v56
	v_lshl_add_u64 v[0:1], v[56:57], 0, s[4:5]
	s_nop 0
	v_addc_co_u32_e32 v3, vcc, 0, v57, vcc
	global_store_dwordx4 v[2:3], v[8:11], off sc1
	global_store_dwordx4 v[0:1], v[12:15], off offset:16 sc1

.LBB0_833:
	s_waitcnt lgkmcnt(0)
	s_barrier
	s_load_dwordx2 s[0:1], s[64:65], 0xc0
	v_lshlrev_b32_e32 v11, 2, v112
	v_xor_b32_e32 v4, 0x80, v11
	v_xor_b32_e32 v5, 64, v11
	v_xor_b32_e32 v6, 32, v11
	v_xor_b32_e32 v7, 16, v11
	v_xor_b32_e32 v8, 8, v11
	v_xor_b32_e32 v9, 4, v11
	s_lshl_b64 s[4:5], s[58:59], 2
	s_lshl_b32 s28, s13, 12
	s_add_i32 s28, s28, 0x10c00
	v_lshl_add_u32 v10, v112, 4, s28
	ds_read_b128 v[156:159], v10
	ds_read_b128 v[160:163], v10 offset:1024
	ds_read_b128 v[164:167], v10 offset:2048
	ds_read_b128 v[168:171], v10 offset:3072
	s_lshl_b32 s29, s13, 2
	s_add_i32 s29, s11, s29
	s_lshl_b32 s29, s29, 11
	s_add_u32 s29, s29, 0x21b2000
	s_add_u32 s40, s62, s29
	s_addc_u32 s41, s63, 0
	v_lshlrev_b32_e32 v0, 5, v112
	v_lshlrev_b32_e32 v1, 4, v112
	v_mov_b32_e32 v2, 0x358637bd
	s_waitcnt lgkmcnt(0)
	s_add_u32 s0, s0, s4
	s_addc_u32 s1, s1, s5
	global_load_dwordx4 v[16:19], v0, s[0:1]
	global_load_dwordx4 v[12:15], v0, s[0:1] offset:16
	v_lshlrev_b32_e32 v182, 16, v156
	v_and_b32_e32 v183, 0xffff0000, v156
	v_lshlrev_b32_e32 v184, 16, v157
	v_and_b32_e32 v185, 0xffff0000, v157
	v_lshlrev_b32_e32 v186, 16, v158
	v_and_b32_e32 v187, 0xffff0000, v158
	v_lshlrev_b32_e32 v188, 16, v159
	v_and_b32_e32 v189, 0xffff0000, v159
	v_mul_f32_e32 v20, v183, v183
	v_fmac_f32_e32 v20, v182, v182
	v_fmac_f32_e32 v20, v184, v184
	v_fmac_f32_e32 v20, v185, v185
	v_mul_f32_e32 v3, v186, v186
	v_add_f32_e32 v20, v3, v20
	v_mul_f32_e32 v3, v187, v187
	v_add_f32_e32 v20, v3, v20
	v_mul_f32_e32 v3, v188, v188
	v_add_f32_e32 v20, v3, v20
	v_mul_f32_e32 v3, v189, v189
	v_add_f32_e32 v20, v3, v20
	v_lshlrev_b32_e32 v182, 16, v160
	v_and_b32_e32 v183, 0xffff0000, v160
	v_lshlrev_b32_e32 v184, 16, v161
	v_and_b32_e32 v185, 0xffff0000, v161
	v_lshlrev_b32_e32 v186, 16, v162
	v_and_b32_e32 v187, 0xffff0000, v162
	v_lshlrev_b32_e32 v188, 16, v163
	v_and_b32_e32 v189, 0xffff0000, v163
	v_mul_f32_e32 v21, v183, v183
	v_fmac_f32_e32 v21, v182, v182
	v_fmac_f32_e32 v21, v184, v184
	v_fmac_f32_e32 v21, v185, v185
	v_mul_f32_e32 v3, v186, v186
	v_add_f32_e32 v21, v3, v21
	v_mul_f32_e32 v3, v187, v187
	v_add_f32_e32 v21, v3, v21
	v_mul_f32_e32 v3, v188, v188
	v_add_f32_e32 v21, v3, v21
	v_mul_f32_e32 v3, v189, v189
	v_add_f32_e32 v21, v3, v21
	v_lshlrev_b32_e32 v182, 16, v164
	v_and_b32_e32 v183, 0xffff0000, v164
	v_lshlrev_b32_e32 v184, 16, v165
	v_and_b32_e32 v185, 0xffff0000, v165
	v_lshlrev_b32_e32 v186, 16, v166
	v_and_b32_e32 v187, 0xffff0000, v166
	v_lshlrev_b32_e32 v188, 16, v167
	v_and_b32_e32 v189, 0xffff0000, v167
	v_mul_f32_e32 v22, v183, v183
	v_fmac_f32_e32 v22, v182, v182
	v_fmac_f32_e32 v22, v184, v184
	v_fmac_f32_e32 v22, v185, v185
	v_mul_f32_e32 v3, v186, v186
	v_add_f32_e32 v22, v3, v22
	v_mul_f32_e32 v3, v187, v187
	v_add_f32_e32 v22, v3, v22
	v_mul_f32_e32 v3, v188, v188
	v_add_f32_e32 v22, v3, v22
	v_mul_f32_e32 v3, v189, v189
	v_add_f32_e32 v22, v3, v22
	v_lshlrev_b32_e32 v182, 16, v168
	v_and_b32_e32 v183, 0xffff0000, v168
	v_lshlrev_b32_e32 v184, 16, v169
	v_and_b32_e32 v185, 0xffff0000, v169
	v_lshlrev_b32_e32 v186, 16, v170
	v_and_b32_e32 v187, 0xffff0000, v170
	v_lshlrev_b32_e32 v188, 16, v171
	v_and_b32_e32 v189, 0xffff0000, v171
	v_mul_f32_e32 v23, v183, v183
	v_fmac_f32_e32 v23, v182, v182
	v_fmac_f32_e32 v23, v184, v184
	v_fmac_f32_e32 v23, v185, v185
	v_mul_f32_e32 v3, v186, v186
	v_add_f32_e32 v23, v3, v23
	v_mul_f32_e32 v3, v187, v187
	v_add_f32_e32 v23, v3, v23
	v_mul_f32_e32 v3, v188, v188
	v_add_f32_e32 v23, v3, v23
	v_mul_f32_e32 v3, v189, v189
	v_add_f32_e32 v23, v3, v23
	ds_bpermute_b32 v24, v4, v20
	ds_bpermute_b32 v25, v4, v21
	ds_bpermute_b32 v26, v4, v22
	ds_bpermute_b32 v27, v4, v23
	s_waitcnt lgkmcnt(3)
	v_add_f32_e32 v20, v20, v24
	s_waitcnt lgkmcnt(2)
	v_add_f32_e32 v21, v21, v25
	s_waitcnt lgkmcnt(1)
	v_add_f32_e32 v22, v22, v26
	s_waitcnt lgkmcnt(0)
	v_add_f32_e32 v23, v23, v27
	ds_bpermute_b32 v24, v5, v20
	ds_bpermute_b32 v25, v5, v21
	ds_bpermute_b32 v26, v5, v22
	ds_bpermute_b32 v27, v5, v23
	s_waitcnt lgkmcnt(3)
	v_add_f32_e32 v20, v20, v24
	s_waitcnt lgkmcnt(2)
	v_add_f32_e32 v21, v21, v25
	s_waitcnt lgkmcnt(1)
	v_add_f32_e32 v22, v22, v26
	s_waitcnt lgkmcnt(0)
	v_add_f32_e32 v23, v23, v27
	ds_bpermute_b32 v24, v6, v20
	ds_bpermute_b32 v25, v6, v21
	ds_bpermute_b32 v26, v6, v22
	ds_bpermute_b32 v27, v6, v23
	s_waitcnt lgkmcnt(3)
	v_add_f32_e32 v20, v20, v24
	s_waitcnt lgkmcnt(2)
	v_add_f32_e32 v21, v21, v25
	s_waitcnt lgkmcnt(1)
	v_add_f32_e32 v22, v22, v26
	s_waitcnt lgkmcnt(0)
	v_add_f32_e32 v23, v23, v27
	ds_bpermute_b32 v24, v7, v20
	ds_bpermute_b32 v25, v7, v21
	ds_bpermute_b32 v26, v7, v22
	ds_bpermute_b32 v27, v7, v23
	s_waitcnt lgkmcnt(3)
	v_add_f32_e32 v20, v20, v24
	s_waitcnt lgkmcnt(2)
	v_add_f32_e32 v21, v21, v25
	s_waitcnt lgkmcnt(1)
	v_add_f32_e32 v22, v22, v26
	s_waitcnt lgkmcnt(0)
	v_add_f32_e32 v23, v23, v27
	ds_bpermute_b32 v24, v8, v20
	ds_bpermute_b32 v25, v8, v21
	ds_bpermute_b32 v26, v8, v22
	ds_bpermute_b32 v27, v8, v23
	s_waitcnt lgkmcnt(3)
	v_add_f32_e32 v20, v20, v24
	s_waitcnt lgkmcnt(2)
	v_add_f32_e32 v21, v21, v25
	s_waitcnt lgkmcnt(1)
	v_add_f32_e32 v22, v22, v26
	s_waitcnt lgkmcnt(0)
	v_add_f32_e32 v23, v23, v27
	ds_bpermute_b32 v24, v9, v20
	ds_bpermute_b32 v25, v9, v21
	ds_bpermute_b32 v26, v9, v22
	ds_bpermute_b32 v27, v9, v23
	s_waitcnt lgkmcnt(3)
	v_add_f32_e32 v20, v20, v24
	s_waitcnt lgkmcnt(2)
	v_add_f32_e32 v21, v21, v25
	s_waitcnt lgkmcnt(1)
	v_add_f32_e32 v22, v22, v26
	s_waitcnt lgkmcnt(0)
	v_add_f32_e32 v23, v23, v27
	v_fmamk_f32 v20, v20, 0x3b000000, v2
	v_fmamk_f32 v21, v21, 0x3b000000, v2
	v_fmamk_f32 v22, v22, 0x3b000000, v2
	v_fmamk_f32 v23, v23, 0x3b000000, v2
	v_rsq_f32_e32 v20, v20
	v_rsq_f32_e32 v21, v21
	v_rsq_f32_e32 v22, v22
	v_rsq_f32_e32 v23, v23
	s_nop 0
	s_waitcnt vmcnt(0)
	v_lshlrev_b32_e32 v182, 16, v156
	v_and_b32_e32 v183, 0xffff0000, v156
	v_lshlrev_b32_e32 v184, 16, v157
	v_and_b32_e32 v185, 0xffff0000, v157
	v_lshlrev_b32_e32 v186, 16, v158
	v_and_b32_e32 v187, 0xffff0000, v158
	v_lshlrev_b32_e32 v188, 16, v159
	v_and_b32_e32 v189, 0xffff0000, v159
	v_mul_f32_e32 v182, v20, v182
	v_mul_f32_e32 v183, v20, v183
	v_mul_f32_e32 v184, v20, v184
	v_mul_f32_e32 v185, v20, v185
	v_mul_f32_e32 v186, v20, v186
	v_mul_f32_e32 v187, v20, v187
	v_mul_f32_e32 v188, v20, v188
	v_mul_f32_e32 v189, v20, v189
	v_mul_f32_e32 v182, v16, v182
	v_mul_f32_e32 v183, v17, v183
	v_mul_f32_e32 v184, v18, v184
	v_mul_f32_e32 v185, v19, v185
	v_mul_f32_e32 v186, v12, v186
	v_mul_f32_e32 v187, v13, v187
	v_mul_f32_e32 v188, v14, v188
	v_mul_f32_e32 v189, v15, v189
	v_cvt_pk_bf16_f32 v190, v182, v183
	v_cvt_pk_bf16_f32 v191, v184, v185
	v_cvt_pk_bf16_f32 v192, v186, v187
	v_cvt_pk_bf16_f32 v193, v188, v189
	global_store_dwordx4 v1, v[190:193], s[40:41] sc1
	v_lshlrev_b32_e32 v182, 16, v160
	v_and_b32_e32 v183, 0xffff0000, v160
	v_lshlrev_b32_e32 v184, 16, v161
	v_and_b32_e32 v185, 0xffff0000, v161
	v_lshlrev_b32_e32 v186, 16, v162
	v_and_b32_e32 v187, 0xffff0000, v162
	v_lshlrev_b32_e32 v188, 16, v163
	v_and_b32_e32 v189, 0xffff0000, v163
	v_mul_f32_e32 v182, v21, v182
	v_mul_f32_e32 v183, v21, v183
	v_mul_f32_e32 v184, v21, v184
	v_mul_f32_e32 v185, v21, v185
	v_mul_f32_e32 v186, v21, v186
	v_mul_f32_e32 v187, v21, v187
	v_mul_f32_e32 v188, v21, v188
	v_mul_f32_e32 v189, v21, v189
	v_mul_f32_e32 v182, v16, v182
	v_mul_f32_e32 v183, v17, v183
	v_mul_f32_e32 v184, v18, v184
	v_mul_f32_e32 v185, v19, v185
	v_mul_f32_e32 v186, v12, v186
	v_mul_f32_e32 v187, v13, v187
	v_mul_f32_e32 v188, v14, v188
	v_mul_f32_e32 v189, v15, v189
	v_cvt_pk_bf16_f32 v190, v182, v183
	v_cvt_pk_bf16_f32 v191, v184, v185
	v_cvt_pk_bf16_f32 v192, v186, v187
	v_cvt_pk_bf16_f32 v193, v188, v189
	global_store_dwordx4 v1, v[190:193], s[40:41] offset:2048 sc1
	s_add_u32 s40, s40, 0x1000
	s_addc_u32 s41, s41, 0
	v_lshlrev_b32_e32 v182, 16, v164
	v_and_b32_e32 v183, 0xffff0000, v164
	v_lshlrev_b32_e32 v184, 16, v165
	v_and_b32_e32 v185, 0xffff0000, v165
	v_lshlrev_b32_e32 v186, 16, v166
	v_and_b32_e32 v187, 0xffff0000, v166
	v_lshlrev_b32_e32 v188, 16, v167
	v_and_b32_e32 v189, 0xffff0000, v167
	v_mul_f32_e32 v182, v22, v182
	v_mul_f32_e32 v183, v22, v183
	v_mul_f32_e32 v184, v22, v184
	v_mul_f32_e32 v185, v22, v185
	v_mul_f32_e32 v186, v22, v186
	v_mul_f32_e32 v187, v22, v187
	v_mul_f32_e32 v188, v22, v188
	v_mul_f32_e32 v189, v22, v189
	v_mul_f32_e32 v182, v16, v182
	v_mul_f32_e32 v183, v17, v183
	v_mul_f32_e32 v184, v18, v184
	v_mul_f32_e32 v185, v19, v185
	v_mul_f32_e32 v186, v12, v186
	v_mul_f32_e32 v187, v13, v187
	v_mul_f32_e32 v188, v14, v188
	v_mul_f32_e32 v189, v15, v189
	v_cvt_pk_bf16_f32 v190, v182, v183
	v_cvt_pk_bf16_f32 v191, v184, v185
	v_cvt_pk_bf16_f32 v192, v186, v187
	v_cvt_pk_bf16_f32 v193, v188, v189
	global_store_dwordx4 v1, v[190:193], s[40:41] sc1
	v_lshlrev_b32_e32 v182, 16, v168
	v_and_b32_e32 v183, 0xffff0000, v168
	v_lshlrev_b32_e32 v184, 16, v169
	v_and_b32_e32 v185, 0xffff0000, v169
	v_lshlrev_b32_e32 v186, 16, v170
	v_and_b32_e32 v187, 0xffff0000, v170
	v_lshlrev_b32_e32 v188, 16, v171
	v_and_b32_e32 v189, 0xffff0000, v171
	v_mul_f32_e32 v182, v23, v182
	v_mul_f32_e32 v183, v23, v183
	v_mul_f32_e32 v184, v23, v184
	v_mul_f32_e32 v185, v23, v185
	v_mul_f32_e32 v186, v23, v186
	v_mul_f32_e32 v187, v23, v187
	v_mul_f32_e32 v188, v23, v188
	v_mul_f32_e32 v189, v23, v189
	v_mul_f32_e32 v182, v16, v182
	v_mul_f32_e32 v183, v17, v183
	v_mul_f32_e32 v184, v18, v184
	v_mul_f32_e32 v185, v19, v185
	v_mul_f32_e32 v186, v12, v186
	v_mul_f32_e32 v187, v13, v187
	v_mul_f32_e32 v188, v14, v188
	v_mul_f32_e32 v189, v15, v189
	v_cvt_pk_bf16_f32 v190, v182, v183
	v_cvt_pk_bf16_f32 v191, v184, v185
	v_cvt_pk_bf16_f32 v192, v186, v187
	v_cvt_pk_bf16_f32 v193, v188, v189
	global_store_dwordx4 v1, v[190:193], s[40:41] offset:2048 sc1
	s_add_i32 s9, s9, s88
	s_cmpk_gt_i32 s9, 0x2ff
	s_barrier
	s_cbranch_scc0 .LBB0_775

.Lht_go:
	v_lshrrev_b32_e32 v72, 3, v204
	v_mul_lo_u32 v53, v72, s74
	v_lshl_add_u32 v53, v51, 4, v53
	s_lshl_b32 s93, s74, 6
	global_load_dwordx4 v[214:217], v53, s[72:73] nt
	v_add_u32_e32 v53, s93, v53
	global_load_dwordx4 v[218:221], v53, s[72:73] nt
	v_add_u32_e32 v53, s93, v53
	global_load_dwordx4 v[222:225], v53, s[72:73] nt
	v_add_u32_e32 v53, s93, v53
	global_load_dwordx4 v[226:229], v53, s[72:73] nt
	v_add_u32_e32 v53, s93, v53
	global_load_dwordx4 v[230:233], v53, s[72:73] nt
	v_add_u32_e32 v53, s93, v53
	global_load_dwordx4 v[234:237], v53, s[72:73] nt
	v_add_u32_e32 v53, s93, v53
	global_load_dwordx4 v[198:201], v53, s[72:73] nt
	v_add_u32_e32 v53, s93, v53
	global_load_dwordx4 v[182:185], v53, s[72:73] nt
	s_lshl_b32 s98, s92, 17
	s_add_u32 s98, s98, 0x21b2000
	s_add_u32 s98, s94, s98
	s_addc_u32 s99, s95, 0
	v_mov_b32_e32 v73, v52
	s_waitcnt vmcnt(7)
	ds_write2_b32 v73, v214, v215 offset1:1
	ds_write2_b32 v73, v216, v217 offset0:2 offset1:3
	v_add_u32_e32 v73, 0x2100, v73
	s_waitcnt vmcnt(6)
	ds_write2_b32 v73, v218, v219 offset1:1
	ds_write2_b32 v73, v220, v221 offset0:2 offset1:3
	v_add_u32_e32 v73, 0x2100, v73
	s_waitcnt vmcnt(5)
	ds_write2_b32 v73, v222, v223 offset1:1
	ds_write2_b32 v73, v224, v225 offset0:2 offset1:3
	v_add_u32_e32 v73, 0x2100, v73
	s_waitcnt vmcnt(4)
	ds_write2_b32 v73, v226, v227 offset1:1
	ds_write2_b32 v73, v228, v229 offset0:2 offset1:3
	v_add_u32_e32 v73, 0x2100, v73
	s_waitcnt vmcnt(3)
	ds_write2_b32 v73, v230, v231 offset1:1
	ds_write2_b32 v73, v232, v233 offset0:2 offset1:3
	v_add_u32_e32 v73, 0x2100, v73
	s_waitcnt vmcnt(2)
	ds_write2_b32 v73, v234, v235 offset1:1
	ds_write2_b32 v73, v236, v237 offset0:2 offset1:3
	v_add_u32_e32 v73, 0x2100, v73
	s_waitcnt vmcnt(1)
	ds_write2_b32 v73, v198, v199 offset1:1
	ds_write2_b32 v73, v200, v201 offset0:2 offset1:3
	v_add_u32_e32 v73, 0x2100, v73
	s_waitcnt vmcnt(0)
	ds_write2_b32 v73, v182, v183 offset1:1
	ds_write2_b32 v73, v184, v185 offset0:2 offset1:3
	s_waitcnt lgkmcnt(0)
	s_barrier
	ds_read_u16 v214, v54 offset:0
	ds_read_u16 v215, v54 offset:132
	ds_read_u16 v216, v54 offset:264
	ds_read_u16 v217, v54 offset:396
	ds_read_u16 v218, v54 offset:528
	ds_read_u16 v219, v54 offset:660
	ds_read_u16 v220, v54 offset:792
	ds_read_u16 v221, v54 offset:924
	ds_read_u16 v222, v54 offset:2
	ds_read_u16 v223, v54 offset:134
	ds_read_u16 v224, v54 offset:266
	ds_read_u16 v225, v54 offset:398
	ds_read_u16 v226, v54 offset:530
	ds_read_u16 v227, v54 offset:662
	ds_read_u16 v228, v54 offset:794
	ds_read_u16 v229, v54 offset:926
	ds_read_u16 v230, v54 offset:4
	ds_read_u16 v231, v54 offset:136
	ds_read_u16 v232, v54 offset:268
	ds_read_u16 v233, v54 offset:400
	ds_read_u16 v234, v54 offset:532
	ds_read_u16 v235, v54 offset:664
	ds_read_u16 v236, v54 offset:796
	ds_read_u16 v237, v54 offset:928
	ds_read_u16 v198, v54 offset:6
	ds_read_u16 v199, v54 offset:138
	ds_read_u16 v200, v54 offset:270
	ds_read_u16 v201, v54 offset:402
	ds_read_u16 v182, v54 offset:534
	ds_read_u16 v183, v54 offset:666
	ds_read_u16 v184, v54 offset:798
	ds_read_u16 v185, v54 offset:930
	s_waitcnt lgkmcnt(15)
	v_lshlrev_b32_e32 v214, 16, v214
	v_lshlrev_b32_e32 v215, 16, v215
	v_lshlrev_b32_e32 v216, 16, v216
	v_lshlrev_b32_e32 v217, 16, v217
	v_lshlrev_b32_e32 v218, 16, v218
	v_lshlrev_b32_e32 v219, 16, v219
	v_lshlrev_b32_e32 v220, 16, v220
	v_lshlrev_b32_e32 v221, 16, v221
	v_mul_f32_e32 v156, v215, v215
	v_fmac_f32_e32 v156, v214, v214
	v_fmac_f32_e32 v156, v216, v216
	v_fmac_f32_e32 v156, v217, v217
	v_mul_f32_e32 v75, v218, v218
	v_add_f32_e32 v156, v156, v75
	v_mul_f32_e32 v75, v219, v219
	v_add_f32_e32 v156, v156, v75
	v_mul_f32_e32 v75, v220, v220
	v_add_f32_e32 v156, v156, v75
	v_mul_f32_e32 v75, v221, v221
	v_add_f32_e32 v156, v156, v75
	s_waitcnt lgkmcnt(15)
	v_lshlrev_b32_e32 v222, 16, v222
	v_lshlrev_b32_e32 v223, 16, v223
	v_lshlrev_b32_e32 v224, 16, v224
	v_lshlrev_b32_e32 v225, 16, v225
	v_lshlrev_b32_e32 v226, 16, v226
	v_lshlrev_b32_e32 v227, 16, v227
	v_lshlrev_b32_e32 v228, 16, v228
	v_lshlrev_b32_e32 v229, 16, v229
	v_mul_f32_e32 v157, v223, v223
	v_fmac_f32_e32 v157, v222, v222
	v_fmac_f32_e32 v157, v224, v224
	v_fmac_f32_e32 v157, v225, v225
	v_mul_f32_e32 v75, v226, v226
	v_add_f32_e32 v157, v157, v75
	v_mul_f32_e32 v75, v227, v227
	v_add_f32_e32 v157, v157, v75
	v_mul_f32_e32 v75, v228, v228
	v_add_f32_e32 v157, v157, v75
	v_mul_f32_e32 v75, v229, v229
	v_add_f32_e32 v157, v157, v75
	s_waitcnt lgkmcnt(8)
	v_lshlrev_b32_e32 v230, 16, v230
	v_lshlrev_b32_e32 v231, 16, v231
	v_lshlrev_b32_e32 v232, 16, v232
	v_lshlrev_b32_e32 v233, 16, v233
	v_lshlrev_b32_e32 v234, 16, v234
	v_lshlrev_b32_e32 v235, 16, v235
	v_lshlrev_b32_e32 v236, 16, v236
	v_lshlrev_b32_e32 v237, 16, v237
	v_mul_f32_e32 v158, v231, v231
	v_fmac_f32_e32 v158, v230, v230
	v_fmac_f32_e32 v158, v232, v232
	v_fmac_f32_e32 v158, v233, v233
	v_mul_f32_e32 v75, v234, v234
	v_add_f32_e32 v158, v158, v75
	v_mul_f32_e32 v75, v235, v235
	v_add_f32_e32 v158, v158, v75
	v_mul_f32_e32 v75, v236, v236
	v_add_f32_e32 v158, v158, v75
	v_mul_f32_e32 v75, v237, v237
	v_add_f32_e32 v158, v158, v75
	s_waitcnt lgkmcnt(0)
	v_lshlrev_b32_e32 v198, 16, v198
	v_lshlrev_b32_e32 v199, 16, v199
	v_lshlrev_b32_e32 v200, 16, v200
	v_lshlrev_b32_e32 v201, 16, v201
	v_lshlrev_b32_e32 v182, 16, v182
	v_lshlrev_b32_e32 v183, 16, v183
	v_lshlrev_b32_e32 v184, 16, v184
	v_lshlrev_b32_e32 v185, 16, v185
	v_mul_f32_e32 v159, v199, v199
	v_fmac_f32_e32 v159, v198, v198
	v_fmac_f32_e32 v159, v200, v200
	v_fmac_f32_e32 v159, v201, v201
	v_mul_f32_e32 v75, v182, v182
	v_add_f32_e32 v159, v159, v75
	v_mul_f32_e32 v75, v183, v183
	v_add_f32_e32 v159, v159, v75
	v_mul_f32_e32 v75, v184, v184
	v_add_f32_e32 v159, v159, v75
	v_mul_f32_e32 v75, v185, v185
	v_add_f32_e32 v159, v159, v75
	ds_bpermute_b32 v164, v57, v156
	ds_bpermute_b32 v165, v57, v157
	ds_bpermute_b32 v166, v57, v158
	ds_bpermute_b32 v167, v57, v159
	s_waitcnt lgkmcnt(3)
	v_add_f32_e32 v156, v156, v164
	s_waitcnt lgkmcnt(2)
	v_add_f32_e32 v157, v157, v165
	s_waitcnt lgkmcnt(1)
	v_add_f32_e32 v158, v158, v166
	s_waitcnt lgkmcnt(0)
	v_add_f32_e32 v159, v159, v167
	ds_bpermute_b32 v164, v58, v156
	ds_bpermute_b32 v165, v58, v157
	ds_bpermute_b32 v166, v58, v158
	ds_bpermute_b32 v167, v58, v159
	s_waitcnt lgkmcnt(3)
	v_add_f32_e32 v156, v156, v164
	s_waitcnt lgkmcnt(2)
	v_add_f32_e32 v157, v157, v165
	s_waitcnt lgkmcnt(1)
	v_add_f32_e32 v158, v158, v166
	s_waitcnt lgkmcnt(0)
	v_add_f32_e32 v159, v159, v167
	ds_bpermute_b32 v164, v59, v156
	ds_bpermute_b32 v165, v59, v157
	ds_bpermute_b32 v166, v59, v158
	ds_bpermute_b32 v167, v59, v159
	s_waitcnt lgkmcnt(3)
	v_add_f32_e32 v156, v156, v164
	s_waitcnt lgkmcnt(2)
	v_add_f32_e32 v157, v157, v165
	s_waitcnt lgkmcnt(1)
	v_add_f32_e32 v158, v158, v166
	s_waitcnt lgkmcnt(0)
	v_add_f32_e32 v159, v159, v167
	ds_bpermute_b32 v164, v60, v156
	ds_bpermute_b32 v165, v60, v157
	ds_bpermute_b32 v166, v60, v158
	ds_bpermute_b32 v167, v60, v159
	s_waitcnt lgkmcnt(3)
	v_add_f32_e32 v156, v156, v164
	s_waitcnt lgkmcnt(2)
	v_add_f32_e32 v157, v157, v165
	s_waitcnt lgkmcnt(1)
	v_add_f32_e32 v158, v158, v166
	s_waitcnt lgkmcnt(0)
	v_add_f32_e32 v159, v159, v167
	ds_bpermute_b32 v164, v61, v156
	ds_bpermute_b32 v165, v61, v157
	ds_bpermute_b32 v166, v61, v158
	ds_bpermute_b32 v167, v61, v159
	s_waitcnt lgkmcnt(3)
	v_add_f32_e32 v156, v156, v164
	s_waitcnt lgkmcnt(2)
	v_add_f32_e32 v157, v157, v165
	s_waitcnt lgkmcnt(1)
	v_add_f32_e32 v158, v158, v166
	s_waitcnt lgkmcnt(0)
	v_add_f32_e32 v159, v159, v167
	ds_bpermute_b32 v164, v62, v156
	ds_bpermute_b32 v165, v62, v157
	ds_bpermute_b32 v166, v62, v158
	ds_bpermute_b32 v167, v62, v159
	s_waitcnt lgkmcnt(3)
	v_add_f32_e32 v156, v156, v164
	s_waitcnt lgkmcnt(2)
	v_add_f32_e32 v157, v157, v165
	s_waitcnt lgkmcnt(1)
	v_add_f32_e32 v158, v158, v166
	s_waitcnt lgkmcnt(0)
	v_add_f32_e32 v159, v159, v167
	v_fmamk_f32 v156, v156, 0x3b000000, v74
	v_fmamk_f32 v157, v157, 0x3b000000, v74
	v_fmamk_f32 v158, v158, 0x3b000000, v74
	v_fmamk_f32 v159, v159, 0x3b000000, v74
	v_rsq_f32_e32 v156, v156
	v_rsq_f32_e32 v157, v157
	v_rsq_f32_e32 v158, v158
	v_rsq_f32_e32 v159, v159
	s_nop 0
	s_waitcnt vmcnt(0)
	v_mul_f32_e32 v186, v156, v214
	v_mul_f32_e32 v187, v156, v215
	v_mul_f32_e32 v188, v156, v216
	v_mul_f32_e32 v189, v156, v217
	v_mul_f32_e32 v190, v156, v218
	v_mul_f32_e32 v191, v156, v219
	v_mul_f32_e32 v192, v156, v220
	v_mul_f32_e32 v193, v156, v221
	v_mul_f32_e32 v186, v64, v186
	v_mul_f32_e32 v187, v65, v187
	v_mul_f32_e32 v188, v66, v188
	v_mul_f32_e32 v189, v67, v189
	v_mul_f32_e32 v190, v68, v190
	v_mul_f32_e32 v191, v69, v191
	v_mul_f32_e32 v192, v70, v192
	v_mul_f32_e32 v193, v71, v193
	v_cvt_pk_bf16_f32 v194, v186, v187
	v_cvt_pk_bf16_f32 v195, v188, v189
	v_cvt_pk_bf16_f32 v196, v190, v191
	v_cvt_pk_bf16_f32 v197, v192, v193
	global_store_dwordx4 v55, v[194:197], s[98:99] sc1
	v_mul_f32_e32 v186, v157, v222
	v_mul_f32_e32 v187, v157, v223
	v_mul_f32_e32 v188, v157, v224
	v_mul_f32_e32 v189, v157, v225
	v_mul_f32_e32 v190, v157, v226
	v_mul_f32_e32 v191, v157, v227
	v_mul_f32_e32 v192, v157, v228
	v_mul_f32_e32 v193, v157, v229
	v_mul_f32_e32 v186, v64, v186
	v_mul_f32_e32 v187, v65, v187
	v_mul_f32_e32 v188, v66, v188
	v_mul_f32_e32 v189, v67, v189
	v_mul_f32_e32 v190, v68, v190
	v_mul_f32_e32 v191, v69, v191
	v_mul_f32_e32 v192, v70, v192
	v_mul_f32_e32 v193, v71, v193
	v_cvt_pk_bf16_f32 v194, v186, v187
	v_cvt_pk_bf16_f32 v195, v188, v189
	v_cvt_pk_bf16_f32 v196, v190, v191
	v_cvt_pk_bf16_f32 v197, v192, v193
	global_store_dwordx4 v55, v[194:197], s[98:99] offset:2048 sc1
	s_add_u32 s98, s98, 0x1000
	s_addc_u32 s99, s99, 0
	v_mul_f32_e32 v186, v158, v230
	v_mul_f32_e32 v187, v158, v231
	v_mul_f32_e32 v188, v158, v232
	v_mul_f32_e32 v189, v158, v233
	v_mul_f32_e32 v190, v158, v234
	v_mul_f32_e32 v191, v158, v235
	v_mul_f32_e32 v192, v158, v236
	v_mul_f32_e32 v193, v158, v237
	v_mul_f32_e32 v186, v64, v186
	v_mul_f32_e32 v187, v65, v187
	v_mul_f32_e32 v188, v66, v188
	v_mul_f32_e32 v189, v67, v189
	v_mul_f32_e32 v190, v68, v190
	v_mul_f32_e32 v191, v69, v191
	v_mul_f32_e32 v192, v70, v192
	v_mul_f32_e32 v193, v71, v193
	v_cvt_pk_bf16_f32 v194, v186, v187
	v_cvt_pk_bf16_f32 v195, v188, v189
	v_cvt_pk_bf16_f32 v196, v190, v191
	v_cvt_pk_bf16_f32 v197, v192, v193
	global_store_dwordx4 v55, v[194:197], s[98:99] sc1
	v_mul_f32_e32 v186, v159, v198
	v_mul_f32_e32 v187, v159, v199
	v_mul_f32_e32 v188, v159, v200
	v_mul_f32_e32 v189, v159, v201
	v_mul_f32_e32 v190, v159, v182
	v_mul_f32_e32 v191, v159, v183
	v_mul_f32_e32 v192, v159, v184
	v_mul_f32_e32 v193, v159, v185
	v_mul_f32_e32 v186, v64, v186
	v_mul_f32_e32 v187, v65, v187
	v_mul_f32_e32 v188, v66, v188
	v_mul_f32_e32 v189, v67, v189
	v_mul_f32_e32 v190, v68, v190
	v_mul_f32_e32 v191, v69, v191
	v_mul_f32_e32 v192, v70, v192
	v_mul_f32_e32 v193, v71, v193
	v_cvt_pk_bf16_f32 v194, v186, v187
	v_cvt_pk_bf16_f32 v195, v188, v189
	v_cvt_pk_bf16_f32 v196, v190, v191
	v_cvt_pk_bf16_f32 v197, v192, v193
	global_store_dwordx4 v55, v[194:197], s[98:99] offset:2048 sc1
	s_add_u32 s98, s98, 0x1000
	s_addc_u32 s99, s99, 0
	ds_read_u16 v214, v54 offset:8
	ds_read_u16 v215, v54 offset:140
	ds_read_u16 v216, v54 offset:272
	ds_read_u16 v217, v54 offset:404
	ds_read_u16 v218, v54 offset:536
	ds_read_u16 v219, v54 offset:668
	ds_read_u16 v220, v54 offset:800
	ds_read_u16 v221, v54 offset:932
	ds_read_u16 v222, v54 offset:10
	ds_read_u16 v223, v54 offset:142
	ds_read_u16 v224, v54 offset:274
	ds_read_u16 v225, v54 offset:406
	ds_read_u16 v226, v54 offset:538
	ds_read_u16 v227, v54 offset:670
	ds_read_u16 v228, v54 offset:802
	ds_read_u16 v229, v54 offset:934
	ds_read_u16 v230, v54 offset:12
	ds_read_u16 v231, v54 offset:144
	ds_read_u16 v232, v54 offset:276
	ds_read_u16 v233, v54 offset:408
	ds_read_u16 v234, v54 offset:540
	ds_read_u16 v235, v54 offset:672
	ds_read_u16 v236, v54 offset:804
	ds_read_u16 v237, v54 offset:936
	ds_read_u16 v198, v54 offset:14
	ds_read_u16 v199, v54 offset:146
	ds_read_u16 v200, v54 offset:278
	ds_read_u16 v201, v54 offset:410
	ds_read_u16 v182, v54 offset:542
	ds_read_u16 v183, v54 offset:674
	ds_read_u16 v184, v54 offset:806
	ds_read_u16 v185, v54 offset:938
	s_waitcnt lgkmcnt(15)
	v_lshlrev_b32_e32 v214, 16, v214
	v_lshlrev_b32_e32 v215, 16, v215
	v_lshlrev_b32_e32 v216, 16, v216
	v_lshlrev_b32_e32 v217, 16, v217
	v_lshlrev_b32_e32 v218, 16, v218
	v_lshlrev_b32_e32 v219, 16, v219
	v_lshlrev_b32_e32 v220, 16, v220
	v_lshlrev_b32_e32 v221, 16, v221
	v_mul_f32_e32 v160, v215, v215
	v_fmac_f32_e32 v160, v214, v214
	v_fmac_f32_e32 v160, v216, v216
	v_fmac_f32_e32 v160, v217, v217
	v_mul_f32_e32 v75, v218, v218
	v_add_f32_e32 v160, v160, v75
	v_mul_f32_e32 v75, v219, v219
	v_add_f32_e32 v160, v160, v75
	v_mul_f32_e32 v75, v220, v220
	v_add_f32_e32 v160, v160, v75
	v_mul_f32_e32 v75, v221, v221
	v_add_f32_e32 v160, v160, v75
	s_waitcnt lgkmcnt(15)
	v_lshlrev_b32_e32 v222, 16, v222
	v_lshlrev_b32_e32 v223, 16, v223
	v_lshlrev_b32_e32 v224, 16, v224
	v_lshlrev_b32_e32 v225, 16, v225
	v_lshlrev_b32_e32 v226, 16, v226
	v_lshlrev_b32_e32 v227, 16, v227
	v_lshlrev_b32_e32 v228, 16, v228
	v_lshlrev_b32_e32 v229, 16, v229
	v_mul_f32_e32 v161, v223, v223
	v_fmac_f32_e32 v161, v222, v222
	v_fmac_f32_e32 v161, v224, v224
	v_fmac_f32_e32 v161, v225, v225
	v_mul_f32_e32 v75, v226, v226
	v_add_f32_e32 v161, v161, v75
	v_mul_f32_e32 v75, v227, v227
	v_add_f32_e32 v161, v161, v75
	v_mul_f32_e32 v75, v228, v228
	v_add_f32_e32 v161, v161, v75
	v_mul_f32_e32 v75, v229, v229
	v_add_f32_e32 v161, v161, v75
	s_waitcnt lgkmcnt(8)
	v_lshlrev_b32_e32 v230, 16, v230
	v_lshlrev_b32_e32 v231, 16, v231
	v_lshlrev_b32_e32 v232, 16, v232
	v_lshlrev_b32_e32 v233, 16, v233
	v_lshlrev_b32_e32 v234, 16, v234
	v_lshlrev_b32_e32 v235, 16, v235
	v_lshlrev_b32_e32 v236, 16, v236
	v_lshlrev_b32_e32 v237, 16, v237
	v_mul_f32_e32 v162, v231, v231
	v_fmac_f32_e32 v162, v230, v230
	v_fmac_f32_e32 v162, v232, v232
	v_fmac_f32_e32 v162, v233, v233
	v_mul_f32_e32 v75, v234, v234
	v_add_f32_e32 v162, v162, v75
	v_mul_f32_e32 v75, v235, v235
	v_add_f32_e32 v162, v162, v75
	v_mul_f32_e32 v75, v236, v236
	v_add_f32_e32 v162, v162, v75
	v_mul_f32_e32 v75, v237, v237
	v_add_f32_e32 v162, v162, v75
	s_waitcnt lgkmcnt(0)
	v_lshlrev_b32_e32 v198, 16, v198
	v_lshlrev_b32_e32 v199, 16, v199
	v_lshlrev_b32_e32 v200, 16, v200
	v_lshlrev_b32_e32 v201, 16, v201
	v_lshlrev_b32_e32 v182, 16, v182
	v_lshlrev_b32_e32 v183, 16, v183
	v_lshlrev_b32_e32 v184, 16, v184
	v_lshlrev_b32_e32 v185, 16, v185
	v_mul_f32_e32 v163, v199, v199
	v_fmac_f32_e32 v163, v198, v198
	v_fmac_f32_e32 v163, v200, v200
	v_fmac_f32_e32 v163, v201, v201
	v_mul_f32_e32 v75, v182, v182
	v_add_f32_e32 v163, v163, v75
	v_mul_f32_e32 v75, v183, v183
	v_add_f32_e32 v163, v163, v75
	v_mul_f32_e32 v75, v184, v184
	v_add_f32_e32 v163, v163, v75
	v_mul_f32_e32 v75, v185, v185
	v_add_f32_e32 v163, v163, v75
	ds_bpermute_b32 v168, v57, v160
	ds_bpermute_b32 v169, v57, v161
	ds_bpermute_b32 v170, v57, v162
	ds_bpermute_b32 v171, v57, v163
	s_waitcnt lgkmcnt(3)
	v_add_f32_e32 v160, v160, v168
	s_waitcnt lgkmcnt(2)
	v_add_f32_e32 v161, v161, v169
	s_waitcnt lgkmcnt(1)
	v_add_f32_e32 v162, v162, v170
	s_waitcnt lgkmcnt(0)
	v_add_f32_e32 v163, v163, v171
	ds_bpermute_b32 v168, v58, v160
	ds_bpermute_b32 v169, v58, v161
	ds_bpermute_b32 v170, v58, v162
	ds_bpermute_b32 v171, v58, v163
	s_waitcnt lgkmcnt(3)
	v_add_f32_e32 v160, v160, v168
	s_waitcnt lgkmcnt(2)
	v_add_f32_e32 v161, v161, v169
	s_waitcnt lgkmcnt(1)
	v_add_f32_e32 v162, v162, v170
	s_waitcnt lgkmcnt(0)
	v_add_f32_e32 v163, v163, v171
	ds_bpermute_b32 v168, v59, v160
	ds_bpermute_b32 v169, v59, v161
	ds_bpermute_b32 v170, v59, v162
	ds_bpermute_b32 v171, v59, v163
	s_waitcnt lgkmcnt(3)
	v_add_f32_e32 v160, v160, v168
	s_waitcnt lgkmcnt(2)
	v_add_f32_e32 v161, v161, v169
	s_waitcnt lgkmcnt(1)
	v_add_f32_e32 v162, v162, v170
	s_waitcnt lgkmcnt(0)
	v_add_f32_e32 v163, v163, v171
	ds_bpermute_b32 v168, v60, v160
	ds_bpermute_b32 v169, v60, v161
	ds_bpermute_b32 v170, v60, v162
	ds_bpermute_b32 v171, v60, v163
	s_waitcnt lgkmcnt(3)
	v_add_f32_e32 v160, v160, v168
	s_waitcnt lgkmcnt(2)
	v_add_f32_e32 v161, v161, v169
	s_waitcnt lgkmcnt(1)
	v_add_f32_e32 v162, v162, v170
	s_waitcnt lgkmcnt(0)
	v_add_f32_e32 v163, v163, v171
	ds_bpermute_b32 v168, v61, v160
	ds_bpermute_b32 v169, v61, v161
	ds_bpermute_b32 v170, v61, v162
	ds_bpermute_b32 v171, v61, v163
	s_waitcnt lgkmcnt(3)
	v_add_f32_e32 v160, v160, v168
	s_waitcnt lgkmcnt(2)
	v_add_f32_e32 v161, v161, v169
	s_waitcnt lgkmcnt(1)
	v_add_f32_e32 v162, v162, v170
	s_waitcnt lgkmcnt(0)
	v_add_f32_e32 v163, v163, v171
	ds_bpermute_b32 v168, v62, v160
	ds_bpermute_b32 v169, v62, v161
	ds_bpermute_b32 v170, v62, v162
	ds_bpermute_b32 v171, v62, v163
	s_waitcnt lgkmcnt(3)
	v_add_f32_e32 v160, v160, v168
	s_waitcnt lgkmcnt(2)
	v_add_f32_e32 v161, v161, v169
	s_waitcnt lgkmcnt(1)
	v_add_f32_e32 v162, v162, v170
	s_waitcnt lgkmcnt(0)
	v_add_f32_e32 v163, v163, v171
	v_fmamk_f32 v160, v160, 0x3b000000, v74
	v_fmamk_f32 v161, v161, 0x3b000000, v74
	v_fmamk_f32 v162, v162, 0x3b000000, v74
	v_fmamk_f32 v163, v163, 0x3b000000, v74
	v_rsq_f32_e32 v160, v160
	v_rsq_f32_e32 v161, v161
	v_rsq_f32_e32 v162, v162
	v_rsq_f32_e32 v163, v163
	s_nop 0
	v_mul_f32_e32 v186, v160, v214
	v_mul_f32_e32 v187, v160, v215
	v_mul_f32_e32 v188, v160, v216
	v_mul_f32_e32 v189, v160, v217
	v_mul_f32_e32 v190, v160, v218
	v_mul_f32_e32 v191, v160, v219
	v_mul_f32_e32 v192, v160, v220
	v_mul_f32_e32 v193, v160, v221
	v_mul_f32_e32 v186, v64, v186
	v_mul_f32_e32 v187, v65, v187
	v_mul_f32_e32 v188, v66, v188
	v_mul_f32_e32 v189, v67, v189
	v_mul_f32_e32 v190, v68, v190
	v_mul_f32_e32 v191, v69, v191
	v_mul_f32_e32 v192, v70, v192
	v_mul_f32_e32 v193, v71, v193
	v_cvt_pk_bf16_f32 v194, v186, v187
	v_cvt_pk_bf16_f32 v195, v188, v189
	v_cvt_pk_bf16_f32 v196, v190, v191
	v_cvt_pk_bf16_f32 v197, v192, v193
	global_store_dwordx4 v55, v[194:197], s[98:99] sc1
	v_mul_f32_e32 v186, v161, v222
	v_mul_f32_e32 v187, v161, v223
	v_mul_f32_e32 v188, v161, v224
	v_mul_f32_e32 v189, v161, v225
	v_mul_f32_e32 v190, v161, v226
	v_mul_f32_e32 v191, v161, v227
	v_mul_f32_e32 v192, v161, v228
	v_mul_f32_e32 v193, v161, v229
	v_mul_f32_e32 v186, v64, v186
	v_mul_f32_e32 v187, v65, v187
	v_mul_f32_e32 v188, v66, v188
	v_mul_f32_e32 v189, v67, v189
	v_mul_f32_e32 v190, v68, v190
	v_mul_f32_e32 v191, v69, v191
	v_mul_f32_e32 v192, v70, v192
	v_mul_f32_e32 v193, v71, v193
	v_cvt_pk_bf16_f32 v194, v186, v187
	v_cvt_pk_bf16_f32 v195, v188, v189
	v_cvt_pk_bf16_f32 v196, v190, v191
	v_cvt_pk_bf16_f32 v197, v192, v193
	global_store_dwordx4 v55, v[194:197], s[98:99] offset:2048 sc1
	s_add_u32 s98, s98, 0x1000
	s_addc_u32 s99, s99, 0
	v_mul_f32_e32 v186, v162, v230
	v_mul_f32_e32 v187, v162, v231
	v_mul_f32_e32 v188, v162, v232
	v_mul_f32_e32 v189, v162, v233
	v_mul_f32_e32 v190, v162, v234
	v_mul_f32_e32 v191, v162, v235
	v_mul_f32_e32 v192, v162, v236
	v_mul_f32_e32 v193, v162, v237
	v_mul_f32_e32 v186, v64, v186
	v_mul_f32_e32 v187, v65, v187
	v_mul_f32_e32 v188, v66, v188
	v_mul_f32_e32 v189, v67, v189
	v_mul_f32_e32 v190, v68, v190
	v_mul_f32_e32 v191, v69, v191
	v_mul_f32_e32 v192, v70, v192
	v_mul_f32_e32 v193, v71, v193
	v_cvt_pk_bf16_f32 v194, v186, v187
	v_cvt_pk_bf16_f32 v195, v188, v189
	v_cvt_pk_bf16_f32 v196, v190, v191
	v_cvt_pk_bf16_f32 v197, v192, v193
	global_store_dwordx4 v55, v[194:197], s[98:99] sc1
	v_mul_f32_e32 v186, v163, v198
	v_mul_f32_e32 v187, v163, v199
	v_mul_f32_e32 v188, v163, v200
	v_mul_f32_e32 v189, v163, v201
	v_mul_f32_e32 v190, v163, v182
	v_mul_f32_e32 v191, v163, v183
	v_mul_f32_e32 v192, v163, v184
	v_mul_f32_e32 v193, v163, v185
	v_mul_f32_e32 v186, v64, v186
	v_mul_f32_e32 v187, v65, v187
	v_mul_f32_e32 v188, v66, v188
	v_mul_f32_e32 v189, v67, v189
	v_mul_f32_e32 v190, v68, v190
	v_mul_f32_e32 v191, v69, v191
	v_mul_f32_e32 v192, v70, v192
	v_mul_f32_e32 v193, v71, v193
	v_cvt_pk_bf16_f32 v194, v186, v187
	v_cvt_pk_bf16_f32 v195, v188, v189
	v_cvt_pk_bf16_f32 v196, v190, v191
	v_cvt_pk_bf16_f32 v197, v192, v193
	global_store_dwordx4 v55, v[194:197], s[98:99] offset:2048 sc1
	s_add_u32 s92, s92, s88
	s_cmp_lt_u32 s92, 0x180
	s_barrier
	s_cbranch_scc1 .Lht_item
